# HGRN V-staging transposed like mLSTM; merge/out prologue drains removed
# speedup vs baseline: 1.1426x; 1.0033x over previous
; __device__ __forceinline__ int tid_() { int x = threadIdx.x; asm volatile("" : "+v"(x)); return x; }
; __device__ __forceinline__ int bid_() { int x = blockIdx.x; asm volatile("" : "+s"(x)); return x; }
; __device__ __forceinline__ void gemm_acc(const bf16_t* __restrict__ A, long lda, const bf16_t* __restrict__ Bt, long ldb, int K, f32x4 (&acc)[4][4], char* lds) {
;     const int tid = tid_(), wid = tid >> 6, lane = tid & 63, wr = wid >> 1, wc = wid & 1, fr = lane & 15, fq = lane >> 4;
;     const int nk = K >> 6;
;     gemm_stage(A, lda, Bt, ldb, 0, lds, tid);
;     asm volatile("s_waitcnt vmcnt(0)" ::: "memory");
;     __syncthreads();
;     for (int kt = 0; kt < nk; ++kt) {
;         char* cur = lds + (kt & 1) * 32768;
;         if (kt + 1 < nk) gemm_stage(A, lda, Bt, ldb, kt + 1, lds + ((kt + 1) & 1) * 32768, tid);
; __device__ void ph_gemm_out(const Params& P, int l, char* lds) {
;     ...
;     for (int item = bid_(); item < 256 * 8; item += gridDim.x) {
;         const int mt = item / 8, nt = item % 8;
;         f32x4 acc[4][4]; zero_acc(acc);
;         gemm_acc(A + (size_t)mt * 128 * DM, DM, Wt + (size_t)nt * 128 * DM, DM, DM, acc, lds);
.Lmy_out_noperm:
	s_lshr_b32 s0, s44, 3
	s_and_b32 s44, s44, 7
	s_ashr_i32 s1, s0, 31
	s_lshl_b64 s[48:49], s[0:1], 18
	v_readlane_b32 s1, v241, 41
	s_waitcnt vmcnt(9)
	v_mov_b32_e32 v20, v178
	s_add_u32 s26, s1, s48
	v_readlane_b32 s1, v241, 42
	s_addc_u32 s27, s1, s49
	v_ashrrev_i32_e32 v2, 3, v20
	s_ashr_i32 s45, s44, 31
	v_lshlrev_b32_e32 v82, 4, v20
	v_xor_b32_e32 v0, v2, v20
	v_ashrrev_i32_e32 v3, 31, v2
	s_lshl_b64 s[28:29], s[44:45], 18
	v_readlane_b32 s50, v241, 43
	v_lshlrev_b64 v[4:5], 11, v[2:3]
	v_lshlrev_b32_e32 v0, 4, v0
	v_add_u32_e32 v3, 0, v82
	v_readlane_b32 s51, v241, 44
	s_add_u32 s50, s50, s28
	v_lshl_add_u64 v[6:7], s[26:27], 0, v[4:5]
	v_and_b32_e32 v0, 0x70, v0
	v_readfirstlane_b32 s1, v3
	s_addc_u32 s51, s51, s29
	v_lshl_add_u64 v[6:7], v[6:7], 0, v[0:1]
	s_mov_b32 m0, s1
	v_lshrrev_b32_e32 v21, 4, v20
	global_load_lds_dwordx4 v[6:7], off
	v_lshl_add_u64 v[6:7], s[50:51], 0, v[4:5]
	v_lshl_add_u64 v[6:7], v[6:7], 0, v[0:1]
	v_add_u32_e32 v0, 0x4000, v3
	v_bfe_u32 v22, v20, 4, 2
	v_readfirstlane_b32 s1, v0
	s_mov_b32 m0, s1
	v_add_u32_e32 v0, 0x1000, v82
	global_load_lds_dwordx4 v[6:7], off
	v_ashrrev_i32_e32 v6, 7, v0
	v_xor_b32_e32 v0, v6, v20
	v_ashrrev_i32_e32 v7, 31, v6
	v_lshlrev_b64 v[8:9], 11, v[6:7]
	v_lshlrev_b32_e32 v0, 4, v0
	v_add_u32_e32 v7, 0x1000, v3
	v_lshl_add_u64 v[10:11], s[26:27], 0, v[8:9]
	v_and_b32_e32 v0, 0x70, v0
	v_readfirstlane_b32 s1, v7
	v_lshl_add_u64 v[10:11], v[10:11], 0, v[0:1]
	s_mov_b32 m0, s1
	v_add_u32_e32 v7, 0x2000, v3
	global_load_lds_dwordx4 v[10:11], off
	v_lshl_add_u64 v[10:11], s[50:51], 0, v[8:9]
	v_lshl_add_u64 v[10:11], v[10:11], 0, v[0:1]
	v_add_u32_e32 v0, 0x5000, v3
	v_bitop3_b32 v2, v2, 7, v20 bitop3:0x48
	v_readfirstlane_b32 s1, v0
	s_mov_b32 m0, s1
	v_add_u32_e32 v0, 0x2000, v82
	global_load_lds_dwordx4 v[10:11], off
	v_ashrrev_i32_e32 v10, 7, v0
	v_xor_b32_e32 v0, v10, v20
	v_ashrrev_i32_e32 v11, 31, v10
	v_lshlrev_b64 v[12:13], 11, v[10:11]
	v_lshlrev_b32_e32 v0, 4, v0
	v_lshl_add_u64 v[14:15], s[26:27], 0, v[12:13]
	v_and_b32_e32 v0, 0x70, v0
	v_readfirstlane_b32 s1, v7
	v_lshl_add_u64 v[14:15], v[14:15], 0, v[0:1]
	s_mov_b32 m0, s1
	v_add_u32_e32 v7, 0x3000, v3
	global_load_lds_dwordx4 v[14:15], off
	v_lshl_add_u64 v[14:15], s[50:51], 0, v[12:13]
	v_lshl_add_u64 v[14:15], v[14:15], 0, v[0:1]
	v_add_u32_e32 v0, 0x6000, v3
	v_bitop3_b32 v6, v6, 7, v20 bitop3:0x48
	v_readfirstlane_b32 s1, v0
	s_mov_b32 m0, s1
	v_add_u32_e32 v0, 0x3000, v82
	global_load_lds_dwordx4 v[14:15], off
	v_ashrrev_i32_e32 v14, 7, v0
	v_xor_b32_e32 v0, v14, v20
	v_ashrrev_i32_e32 v15, 31, v14
	v_lshlrev_b64 v[16:17], 11, v[14:15]
	v_lshlrev_b32_e32 v0, 4, v0
	v_lshl_add_u64 v[18:19], s[26:27], 0, v[16:17]
	v_and_b32_e32 v0, 0x70, v0
	v_readfirstlane_b32 s1, v7
	v_lshl_add_u64 v[18:19], v[18:19], 0, v[0:1]
	s_mov_b32 m0, s1
	v_lshlrev_b32_e32 v6, 4, v6
	global_load_lds_dwordx4 v[18:19], off
	v_lshl_add_u64 v[18:19], s[50:51], 0, v[16:17]
	v_lshl_add_u64 v[18:19], v[18:19], 0, v[0:1]
	v_add_u32_e32 v0, 0x7000, v3
	v_lshrrev_b32_e32 v3, 1, v20
	v_readfirstlane_b32 s1, v0
	s_mov_b32 m0, s1
	v_and_b32_e32 v0, 15, v20
	global_load_lds_dwordx4 v[18:19], off
	v_and_or_b32 v0, v3, s46, v0
	v_and_b32_e32 v3, 7, v20
	v_bitop3_b32 v7, v21, v3, 3 bitop3:0x6c
	v_bitop3_b32 v3, v22, v3, 4 bitop3:0x36
	v_lshlrev_b32_e32 v85, 4, v7
	v_lshlrev_b32_e32 v84, 4, v3
	v_lshlrev_b32_e32 v7, 4, v2
	v_lshl_add_u64 v[2:3], s[48:49], 0, v[8:9]
	v_or_b32_e32 v2, v2, v6
	v_bitop3_b32 v10, v10, 7, v20 bitop3:0x48
	v_lshl_add_u64 v[68:69], s[40:41], 0, v[2:3]
	v_lshl_add_u64 v[2:3], s[48:49], 0, v[12:13]
	v_lshlrev_b32_e32 v10, 4, v10
	v_or_b32_e32 v2, v2, v10
	v_bitop3_b32 v11, v14, 7, v20 bitop3:0x48
	v_lshl_add_u64 v[70:71], s[40:41], 0, v[2:3]
	v_lshl_add_u64 v[2:3], s[48:49], 0, v[16:17]
	v_lshlrev_b32_e32 v11, 4, v11
	v_or_b32_e32 v2, v2, v11
	v_lshl_add_u64 v[72:73], s[40:41], 0, v[2:3]
	v_lshl_add_u64 v[2:3], s[28:29], 0, v[4:5]
	v_or_b32_e32 v2, v2, v7
	v_lshl_add_u64 v[74:75], s[42:43], 0, v[2:3]
	v_lshl_add_u64 v[2:3], s[28:29], 0, v[8:9]
	v_or_b32_e32 v2, v2, v6
	v_lshl_add_u64 v[76:77], s[42:43], 0, v[2:3]
	v_lshl_add_u64 v[2:3], s[28:29], 0, v[12:13]
	v_or_b32_e32 v2, v2, v10
	v_lshl_add_u64 v[78:79], s[42:43], 0, v[2:3]
	v_lshl_add_u64 v[2:3], s[28:29], 0, v[16:17]
	v_lshl_add_u64 v[18:19], s[48:49], 0, v[4:5]
	v_or_b32_e32 v2, v2, v11
	v_lshlrev_b32_e32 v83, 7, v0
	v_lshlrev_b32_e32 v0, 7, v20
	v_or_b32_e32 v18, v18, v7
	v_lshl_add_u64 v[80:81], s[42:43], 0, v[2:3]
	v_mov_b32_e32 v2, 0
	v_and_b32_e32 v0, 0x2780, v0
	v_lshl_add_u64 v[66:67], s[40:41], 0, v[18:19]
	s_mov_b64 s[28:29], 0
	s_mov_b32 s1, 0x8000
	v_mov_b32_e32 v3, v2
	v_mov_b32_e32 v4, v2
	v_mov_b32_e32 v5, v2
	v_mov_b32_e32 v6, v2
	v_mov_b32_e32 v7, v2
	v_mov_b32_e32 v8, v2
	v_mov_b32_e32 v9, v2
	v_mov_b32_e32 v10, v2
	v_mov_b32_e32 v11, v2
	v_mov_b32_e32 v12, v2
	v_mov_b32_e32 v13, v2
	v_mov_b32_e32 v14, v2
	v_mov_b32_e32 v15, v2
	v_mov_b32_e32 v16, v2
	v_mov_b32_e32 v17, v2
	v_mov_b32_e32 v18, v2
	v_mov_b32_e32 v19, v2
	v_mov_b32_e32 v20, v2
	v_mov_b32_e32 v21, v2
	v_mov_b32_e32 v22, v2
	v_mov_b32_e32 v23, v2
	v_mov_b32_e32 v24, v2
	v_mov_b32_e32 v25, v2
	v_mov_b32_e32 v26, v2
	v_mov_b32_e32 v27, v2
	v_mov_b32_e32 v28, v2
	v_mov_b32_e32 v29, v2
	v_mov_b32_e32 v30, v2
	v_mov_b32_e32 v31, v2
	v_mov_b32_e32 v32, v2
	v_mov_b32_e32 v33, v2
	v_mov_b32_e32 v34, v2
	v_mov_b32_e32 v35, v2
	v_mov_b32_e32 v36, v2
	v_mov_b32_e32 v37, v2
	v_mov_b32_e32 v38, v2
	v_mov_b32_e32 v39, v2
	v_mov_b32_e32 v40, v2
	v_mov_b32_e32 v41, v2
	v_mov_b32_e32 v42, v2
	v_mov_b32_e32 v43, v2
	v_mov_b32_e32 v44, v2
	v_mov_b32_e32 v45, v2
	v_mov_b32_e32 v46, v2
	v_mov_b32_e32 v47, v2
	v_mov_b32_e32 v48, v2
	v_mov_b32_e32 v49, v2
	v_mov_b32_e32 v50, v2
	v_mov_b32_e32 v51, v2
	v_mov_b32_e32 v52, v2
	v_mov_b32_e32 v53, v2
	v_mov_b32_e32 v54, v2
	v_mov_b32_e32 v55, v2
	v_mov_b32_e32 v56, v2
	v_mov_b32_e32 v57, v2
	v_mov_b32_e32 v58, v2
	v_mov_b32_e32 v59, v2
	v_mov_b32_e32 v60, v2
	v_mov_b32_e32 v61, v2
	v_mov_b32_e32 v62, v2
	v_mov_b32_e32 v63, v2
	v_mov_b32_e32 v64, v2
	v_mov_b32_e32 v65, v2
	s_waitcnt lgkmcnt(0)
	v_readfirstlane_b32 s27, v82
	s_mov_b64 s[28:29], 0
	s_add_i32 m0, s27, 0x8000
	s_nop 0
	global_load_lds_dwordx4 v[66:67], off
	s_add_i32 m0, s27, 0xc000
	s_nop 0
	global_load_lds_dwordx4 v[74:75], off
	s_add_i32 m0, s27, 0x9000
	s_nop 0
	global_load_lds_dwordx4 v[68:69], off
	s_add_i32 m0, s27, 0xd000
	s_nop 0
	global_load_lds_dwordx4 v[76:77], off
	s_add_i32 m0, s27, 0xa000
	s_nop 0
	global_load_lds_dwordx4 v[70:71], off
	s_add_i32 m0, s27, 0xe000
	s_nop 0
	global_load_lds_dwordx4 v[78:79], off
	s_add_i32 m0, s27, 0xb000
	s_nop 0
	global_load_lds_dwordx4 v[72:73], off
	s_add_i32 m0, s27, 0xf000
	s_nop 0
	global_load_lds_dwordx4 v[80:81], off
	s_movk_i32 s28, 0x80
	s_mov_b32 s1, 0

; __device__ __forceinline__ int tid_() { int x = threadIdx.x; asm volatile("" : "+v"(x)); return x; }
; __device__ __forceinline__ void gemm_acc(const bf16_t* __restrict__ A, long lda, const bf16_t* __restrict__ Bt, long ldb, int K, f32x4 (&acc)[4][4], char* lds) {
;     const int tid = tid_(), wid = tid >> 6, lane = tid & 63, wr = wid >> 1, wc = wid & 1, fr = lane & 15, fq = lane >> 4;
;     const int nk = K >> 6;
;     gemm_stage(A, lda, Bt, ldb, 0, lds, tid);
;     asm volatile("s_waitcnt vmcnt(0)" ::: "memory");
;     __syncthreads();
;     for (int kt = 0; kt < nk; ++kt) {
;         char* cur = lds + (kt & 1) * 32768;
;         if (kt + 1 < nk) gemm_stage(A, lda, Bt, ldb, kt + 1, lds + ((kt + 1) & 1) * 32768, tid);
; __device__ void ph_gemm_merge(const Params& P, char* lds) {
;     ...
;                 f32x4 acc[4][4]; zero_acc(acc);
;                 gemm_acc(U + (size_t)mt * 128 * DM, DM, Wt + (size_t)(GATE_ROW0 + n * 1024 + nt * 128) * DM, DM, DM, acc, lds);
.LBB0_310:
	s_ashr_i32 s53, s52, 31
	s_lshl_b64 s[28:29], s[52:53], 11
	s_lshl_b32 s53, s63, 10
	s_waitcnt vmcnt(9)
	v_mov_b32_e32 v20, v178
	s_add_i32 s26, s30, s53
	s_ashr_i32 s27, s26, 31
	v_ashrrev_i32_e32 v2, 3, v20
	v_lshlrev_b32_e32 v82, 4, v20
	v_xor_b32_e32 v0, v2, v20
	v_ashrrev_i32_e32 v3, 31, v2
	s_lshl_b64 s[26:27], s[26:27], 11
	v_lshlrev_b64 v[4:5], 11, v[2:3]
	v_lshlrev_b32_e32 v0, 4, v0
	v_add_u32_e32 v3, 0, v82
	s_add_u32 s26, s74, s26
	v_lshl_add_u64 v[6:7], s[48:49], 0, v[4:5]
	v_and_b32_e32 v0, 0x70, v0
	v_readfirstlane_b32 s24, v3
	s_addc_u32 s27, s75, s27
	v_lshl_add_u64 v[6:7], v[6:7], 0, v[0:1]
	s_mov_b32 m0, s24
	v_bitop3_b32 v2, v2, 7, v20 bitop3:0x48
	global_load_lds_dwordx4 v[6:7], off
	v_lshl_add_u64 v[6:7], s[26:27], 0, v[4:5]
	v_lshl_add_u64 v[6:7], v[6:7], 0, v[0:1]
	v_add_u32_e32 v0, 0x4000, v3
	v_lshl_or_b32 v4, v2, 4, v4
	v_readfirstlane_b32 s24, v0
	s_mov_b32 m0, s24
	v_add_u32_e32 v0, 0x1000, v82
	global_load_lds_dwordx4 v[6:7], off
	v_ashrrev_i32_e32 v6, 7, v0
	v_xor_b32_e32 v0, v6, v20
	v_ashrrev_i32_e32 v7, 31, v6
	v_lshlrev_b64 v[8:9], 11, v[6:7]
	v_lshlrev_b32_e32 v0, 4, v0
	v_add_u32_e32 v7, 0x1000, v3
	v_lshl_add_u64 v[10:11], s[48:49], 0, v[8:9]
	v_and_b32_e32 v0, 0x70, v0
	v_readfirstlane_b32 s24, v7
	v_lshl_add_u64 v[10:11], v[10:11], 0, v[0:1]
	s_mov_b32 m0, s24
	v_add_u32_e32 v7, 0x2000, v3
	global_load_lds_dwordx4 v[10:11], off
	v_lshl_add_u64 v[10:11], s[26:27], 0, v[8:9]
	v_lshl_add_u64 v[10:11], v[10:11], 0, v[0:1]
	v_add_u32_e32 v0, 0x5000, v3
	v_bitop3_b32 v2, v6, 7, v20 bitop3:0x48
	v_readfirstlane_b32 s24, v0
	s_mov_b32 m0, s24
	v_add_u32_e32 v0, 0x2000, v82
	global_load_lds_dwordx4 v[10:11], off
	v_ashrrev_i32_e32 v10, 7, v0
	v_xor_b32_e32 v0, v10, v20
	v_ashrrev_i32_e32 v11, 31, v10
	v_lshlrev_b64 v[12:13], 11, v[10:11]
	v_lshlrev_b32_e32 v0, 4, v0
	v_lshl_add_u64 v[14:15], s[48:49], 0, v[12:13]
	v_and_b32_e32 v0, 0x70, v0
	v_readfirstlane_b32 s24, v7
	v_lshl_add_u64 v[14:15], v[14:15], 0, v[0:1]
	s_mov_b32 m0, s24
	v_add_u32_e32 v7, 0x3000, v3
	global_load_lds_dwordx4 v[14:15], off
	v_lshl_add_u64 v[14:15], s[26:27], 0, v[12:13]
	v_lshl_add_u64 v[14:15], v[14:15], 0, v[0:1]
	v_add_u32_e32 v0, 0x6000, v3
	v_lshl_or_b32 v8, v2, 4, v8
	v_readfirstlane_b32 s24, v0
	s_mov_b32 m0, s24
	v_add_u32_e32 v0, 0x3000, v82
	global_load_lds_dwordx4 v[14:15], off
	v_ashrrev_i32_e32 v14, 7, v0
	v_xor_b32_e32 v0, v14, v20
	v_ashrrev_i32_e32 v15, 31, v14
	v_lshlrev_b64 v[16:17], 11, v[14:15]
	v_lshlrev_b32_e32 v0, 4, v0
	v_lshl_add_u64 v[18:19], s[48:49], 0, v[16:17]
	v_and_b32_e32 v0, 0x70, v0
	v_readfirstlane_b32 s24, v7
	v_lshl_add_u64 v[18:19], v[18:19], 0, v[0:1]
	s_mov_b32 m0, s24
	v_bitop3_b32 v2, v10, 7, v20 bitop3:0x48
	global_load_lds_dwordx4 v[18:19], off
	v_lshl_add_u64 v[18:19], s[26:27], 0, v[16:17]
	v_lshl_add_u64 v[18:19], v[18:19], 0, v[0:1]
	v_add_u32_e32 v0, 0x7000, v3
	v_lshrrev_b32_e32 v3, 1, v20
	v_readfirstlane_b32 s24, v0
	s_mov_b32 m0, s24
	v_and_b32_e32 v0, 15, v20
	global_load_lds_dwordx4 v[18:19], off
	v_readlane_b32 s24, v239, 59
	v_lshrrev_b32_e32 v21, 4, v20
	v_bfe_u32 v22, v20, 4, 2
	v_and_or_b32 v0, v3, s40, v0
	v_and_b32_e32 v3, 7, v20
	v_lshl_or_b32 v12, v2, 4, v12
	v_bitop3_b32 v2, v14, 7, v20 bitop3:0x48
	s_add_u32 s26, s24, s28
	v_readlane_b32 s24, v239, 60
	v_bitop3_b32 v7, v21, v3, 3 bitop3:0x6c
	v_lshlrev_b32_e32 v83, 7, v0
	v_lshlrev_b32_e32 v0, 7, v20
	v_bitop3_b32 v3, v22, v3, 4 bitop3:0x36
	v_lshl_or_b32 v16, v2, 4, v16
	s_addc_u32 s27, s24, s29
	v_lshlrev_b32_e32 v85, 4, v7
	v_and_b32_e32 v0, 0x2780, v0
	v_lshlrev_b32_e32 v84, 4, v3
	v_lshl_add_u64 v[66:67], s[50:51], 0, v[4:5]
	v_lshl_add_u64 v[68:69], s[50:51], 0, v[8:9]
	v_lshl_add_u64 v[70:71], s[50:51], 0, v[12:13]
	v_lshl_add_u64 v[72:73], s[50:51], 0, v[16:17]
	v_lshl_add_u64 v[74:75], s[26:27], 0, v[4:5]
	v_lshl_add_u64 v[76:77], s[26:27], 0, v[8:9]
	v_lshl_add_u64 v[78:79], s[26:27], 0, v[12:13]
	v_lshl_add_u64 v[80:81], s[26:27], 0, v[16:17]
	s_mov_b64 s[28:29], 0
	s_mov_b32 s24, 0x8000
	v_mov_b32_e32 v2, 0
	v_mov_b32_e32 v3, v189
	v_mov_b32_e32 v4, v189
	v_mov_b32_e32 v5, v189
	v_mov_b32_e32 v6, 0
	v_mov_b32_e32 v7, v189
	v_mov_b32_e32 v8, v189
	v_mov_b32_e32 v9, v189
	v_mov_b32_e32 v10, 0
	v_mov_b32_e32 v11, v189
	v_mov_b32_e32 v12, v189
	v_mov_b32_e32 v13, v189
	v_mov_b32_e32 v14, 0
	v_mov_b32_e32 v15, v189
	v_mov_b32_e32 v16, v189
	v_mov_b32_e32 v17, v189
	v_mov_b32_e32 v18, 0
	v_mov_b32_e32 v19, v189
	v_mov_b32_e32 v20, v189
	v_mov_b32_e32 v21, v189
	v_mov_b32_e32 v22, 0
	v_mov_b32_e32 v23, v189
	v_mov_b32_e32 v24, v189
	v_mov_b32_e32 v25, v189
	v_mov_b32_e32 v26, 0
	v_mov_b32_e32 v27, v189
	v_mov_b32_e32 v28, v189
	v_mov_b32_e32 v29, v189
	v_mov_b32_e32 v30, 0
	v_mov_b32_e32 v31, v189
	v_mov_b32_e32 v32, v189
	v_mov_b32_e32 v33, v189
	v_mov_b32_e32 v34, 0
	v_mov_b32_e32 v35, v189
	v_mov_b32_e32 v36, v189
	v_mov_b32_e32 v37, v189
	v_mov_b32_e32 v38, 0
	v_mov_b32_e32 v39, v189
	v_mov_b32_e32 v40, v189
	v_mov_b32_e32 v41, v189
	v_mov_b32_e32 v42, 0
	v_mov_b32_e32 v43, v189
	v_mov_b32_e32 v44, v189
	v_mov_b32_e32 v45, v189
	v_mov_b32_e32 v46, 0
	v_mov_b32_e32 v47, v189
	v_mov_b32_e32 v48, v189
	v_mov_b32_e32 v49, v189
	v_mov_b32_e32 v50, 0
	v_mov_b32_e32 v51, v189
	v_mov_b32_e32 v52, v189
	v_mov_b32_e32 v53, v189
	v_mov_b32_e32 v54, 0
	v_mov_b32_e32 v55, v189
	v_mov_b32_e32 v56, v189
	v_mov_b32_e32 v57, v189
	v_mov_b32_e32 v58, 0
	v_mov_b32_e32 v59, v189
	v_mov_b32_e32 v60, v189
	v_mov_b32_e32 v61, v189
	v_mov_b32_e32 v62, 0
	v_mov_b32_e32 v63, v189
	v_mov_b32_e32 v64, v189
	v_mov_b32_e32 v65, v189
	s_waitcnt lgkmcnt(0)
	v_readfirstlane_b32 s27, v82
	s_mov_b64 s[28:29], 0
	s_add_i32 m0, s27, 0x8000
	s_nop 0
	global_load_lds_dwordx4 v[66:67], off
	s_add_i32 m0, s27, 0xc000
	s_nop 0
	global_load_lds_dwordx4 v[74:75], off
	s_add_i32 m0, s27, 0x9000
	s_nop 0
	global_load_lds_dwordx4 v[68:69], off
	s_add_i32 m0, s27, 0xd000
	s_nop 0
	global_load_lds_dwordx4 v[76:77], off
	s_add_i32 m0, s27, 0xa000
	s_nop 0
	global_load_lds_dwordx4 v[70:71], off
	s_add_i32 m0, s27, 0xe000
	s_nop 0
	global_load_lds_dwordx4 v[78:79], off
	s_add_i32 m0, s27, 0xb000
	s_nop 0
	global_load_lds_dwordx4 v[72:73], off
	s_add_i32 m0, s27, 0xf000
	s_nop 0
	global_load_lds_dwordx4 v[80:81], off
	s_movk_i32 s28, 0x80
	s_mov_b32 s24, 0

; __device__ __forceinline__ int tid_() { int x = threadIdx.x; asm volatile("" : "+v"(x)); return x; }
; __device__ void mx_hgrn(const Params& P, int l, int item, char* lds) {
;     const int tid = tid_(), wid = tid >> 6, lane = tid & 63, fr = lane & 15, fq = lane >> 4;
;     const int b = item >> 4, h = (item >> 2) & 3, half = (item >> 1) & 1, dsel = item & 1;
;     const bf16_t* pr = (const bf16_t*)(P.ws + OFF_PREST) + (size_t)b * SQ * PREST_LD + HG_O;
;     bf16_t* YD = (bf16_t*)(P.ws + (dsel ? OFF_YD : OFF_Y0)) + (size_t)b * SQ * 512 + h * 128 + half * 64;
;     bf16_t* QT = (bf16_t*)lds; bf16_t* KT = QT + 64 * 136; bf16_t* ATT = KT + 128 * 72; bf16_t* VT = ATT + 64 * 72; bf16_t* ST = VT + 64 * 72;
;     float* TOT = (float*)(ST + 64 * 136);
;     const int dk = tid & 127, hf = tid >> 7;
;     const int i = wid * 16 + fr;
; #pragma unroll 1
;     for (int d = dsel; d <= dsel; ++d) {
;         const float lbv = ((const float*)(P.ws + OFF_LB))[(l * 2 + d) * 512 + h * 128 + dk], oml = 1.f - lbv;
;         f32x4 Sacc[2][4];
; #pragma unroll
;         for (int a = 0; a < 2; ++a)
; #pragma unroll
;             for (int dt = 0; dt < 4; ++dt) Sacc[a][dt] = (f32x4){0.f, 0.f, 0.f, 0.f};
;         __syncthreads();
;         for (int e = tid; e < 64 * 136 / 2; e += NT) ((unsigned*)ST)[e] = 0u;
;         __syncthreads();
;         u32x4 pff[4], pfq[4], pfv[2];
;         auto hg_load = [&](int cc) {
;             const int t0 = d ? SQ - 64 * (cc + 1) : 64 * cc;
; #pragma unroll
;             for (int it = 0; it < 4; ++it) {
;                 const int vi = tid + 256 * it, ii = vi >> 4, e = vi & 15, t = TROW(ii);
;                 pff[it] = *(const u32x4*)(pr + (size_t)t * PREST_LD + 512 * (1 + d) + h * 128 + e * 8);
;                 pfq[it] = *(const u32x4*)(pr + (size_t)t * PREST_LD + h * 128 + e * 8);
;             }
; #pragma unroll
;             for (int it = 0; it < 2; ++it) {
;                 const int vi = tid + 256 * it, ii = vi >> 3, e = vi & 7, t = TROW(ii);
;                 pfv[it] = *(const u32x4*)(pr + (size_t)t * PREST_LD + 1536 + h * 128 + half * 64 + e * 8);
;             }
;         };
;         hg_load(0);
.LBB0_515:
	s_or_b64 exec, exec, s[0:1]
	s_ashr_i32 s28, s30, 4
	s_ashr_i32 s29, s28, 31
	s_mul_i32 s1, s28, 0x1480000
	s_mul_hi_i32 s0, s28, 0x1480000
	s_add_u32 s1, s74, s1
	s_addc_u32 s26, s75, s0
	s_add_u32 s0, s1, 0xa001500
	s_addc_u32 s1, s26, 0
	s_cmp_eq_u32 s24, 0
	s_cselect_b64 vcc, -1, 0
	s_and_b64 s[40:41], vcc, exec
	s_mov_b32 s24, 0x22800000
	s_cselect_b32 s24, 0x24800000, s24
	s_add_u32 s24, s74, s24
	s_addc_u32 s26, s75, 0
	s_lshl_b64 s[28:29], s[28:29], 21
	s_add_u32 s27, s24, s28
	s_addc_u32 s26, s26, s29
	s_lshl_b32 s24, s21, 1
	s_add_u32 s27, s27, s24
	s_addc_u32 s26, s26, 0
	s_and_b32 s28, s38, 64
	s_lshl_b32 s28, s28, 1
	s_add_u32 s40, s27, s28
	s_addc_u32 s41, s26, 0
	s_waitcnt vmcnt(13)
	v_ashrrev_i32_e32 v7, 7, v42
	s_movk_i32 s26, 0x2200
	v_lshlrev_b32_e32 v0, 3, v42
	v_ashrrev_i32_e32 v43, 6, v42
	v_and_b32_e32 v45, 15, v42
	v_mul_lo_u32 v49, v7, s26
	s_movk_i32 s26, 0x80
	s_waitcnt vmcnt(6)
	v_and_b32_e32 v34, 56, v0
	v_lshl_or_b32 v126, v43, 4, v45
	v_add_u32_e32 v8, 0x200, v42
	v_readlane_b32 s27, v238, 9
	v_cmp_gt_u32_e64 s[38:39], s26, v42
	s_movk_i32 s26, 0x110
	v_mul_u32_u24_e32 v4, 0x90, v34
	v_mul_u32_u24_e32 v3, 0x90, v2
	v_bfe_u32 v5, v42, 4, 2
	v_ashrrev_i32_e32 v125, 4, v42
	v_and_b32_e32 v44, 0x78, v0
	v_add_u32_e32 v0, 0x100, v42
	v_ashrrev_i32_e32 v128, 4, v8
	v_add_u32_e32 v8, 0x300, v42
	v_lshlrev_b32_e32 v48, 1, v2
	v_lshl_add_u32 v134, v2, 2, s27
	v_mul_lo_u32 v2, v126, s26
	v_sub_u32_e32 v6, 0x7ff, v125
	v_ashrrev_i32_e32 v127, 4, v0
	v_ashrrev_i32_e32 v129, 4, v8
	v_add_u32_e32 v47, 0, v4
	v_add_u32_e32 v2, 0, v2
	v_lshlrev_b32_e32 v74, 3, v5
	v_lshlrev_b32_e32 v4, 4, v5
	v_lshlrev_b32_e32 v50, 2, v5
	v_lshlrev_b32_e32 v5, 7, v126
	v_cndmask_b32_e32 v6, v6, v125, vcc
	v_add_u32_e32 v135, v2, v4
	v_sub_u32_e32 v2, v2, v5
	v_mov_b32_e32 v75, v1
	v_mov_b64_e32 v[36:37], s[0:1]
	v_sub_u32_e32 v10, 0x7ff, v127
	v_sub_u32_e32 v18, 0x7ff, v128
	v_sub_u32_e32 v26, 0x7ff, v129
	v_add_u32_e32 v137, v2, v74
	v_add_u32_e32 v51, 0, v3
	v_lshl_add_u64 v[76:77], s[40:41], 0, v[74:75]
	v_mad_i64_i32 v[2:3], s[40:41], v6, s3, v[36:37]
	v_cndmask_b32_e32 v10, v10, v127, vcc
	v_cndmask_b32_e32 v18, v18, v128, vcc
	v_cndmask_b32_e32 v26, v26, v129, vcc
	s_lshl_b32 s40, s35, 1
	s_mov_b32 s41, s25
	v_mad_i64_i32 v[10:11], s[42:43], v10, s3, v[36:37]
	v_mad_i64_i32 v[18:19], s[42:43], v18, s3, v[36:37]
	v_mad_i64_i32 v[26:27], s[42:43], v26, s3, v[36:37]
	v_add_u32_e32 v136, 0, v4
	v_add_u32_e32 v53, s27, v4
	v_lshl_add_u64 v[4:5], v[2:3], 0, s[40:41]
	v_lshl_add_u64 v[12:13], v[10:11], 0, s[40:41]
	v_lshl_add_u64 v[20:21], v[18:19], 0, s[40:41]
	v_lshl_add_u64 v[28:29], v[26:27], 0, s[40:41]
	v_and_b32_e32 v130, 63, v178
	v_and_b32_e32 v131, 63, v178
	v_lshlrev_b32_e32 v0, 1, v44
	v_lshl_add_u64 v[4:5], v[4:5], 0, s[24:25]
	v_lshl_add_u64 v[2:3], v[2:3], 0, s[24:25]
	v_lshl_add_u64 v[12:13], v[12:13], 0, s[24:25]
	v_lshl_add_u64 v[10:11], v[10:11], 0, s[24:25]
	v_lshl_add_u64 v[20:21], v[20:21], 0, s[24:25]
	v_lshl_add_u64 v[18:19], v[18:19], 0, s[24:25]
	v_lshl_add_u64 v[28:29], v[28:29], 0, s[24:25]
	v_lshl_add_u64 v[26:27], v[26:27], 0, s[24:25]
	v_add_u32_e32 v46, 0, v0
	v_lshlrev_b32_e32 v52, 6, v7
	v_lshl_add_u64 v[4:5], v[4:5], 0, v[0:1]
	v_lshl_add_u64 v[6:7], v[2:3], 0, v[0:1]
	v_lshl_add_u64 v[12:13], v[12:13], 0, v[0:1]
	v_lshl_add_u64 v[14:15], v[10:11], 0, v[0:1]
	v_lshl_add_u64 v[20:21], v[20:21], 0, v[0:1]
	v_lshl_add_u64 v[22:23], v[18:19], 0, v[0:1]
	v_lshl_add_u64 v[28:29], v[28:29], 0, v[0:1]
	v_lshl_add_u64 v[30:31], v[26:27], 0, v[0:1]
	v_sub_u32_e32 v0, 0x7ff, v130
	v_cndmask_b32_e32 v0, v0, v130, vcc
	s_waitcnt vmcnt(5)
	v_mad_i64_i32 v[38:39], s[40:41], v0, s3, v[36:37]
	s_mov_b32 s29, s25
	v_lshl_add_u64 v[38:39], v[38:39], 0, s[24:25]
	v_sub_u32_e32 v40, 0x7ff, v131
	v_lshl_add_u64 v[38:39], v[38:39], 0, s[28:29]
	v_lshrrev_b32_e32 v0, 6, v178
	v_lshlrev_b32_e32 v0, 4, v0
	v_lshl_add_u64 v[34:35], v[38:39], 0, v[0:1]
	v_cndmask_b32_e32 v38, v40, v131, vcc
	v_mad_i64_i32 v[36:37], s[40:41], v38, s3, v[36:37]
	v_lshl_add_u64 v[36:37], v[36:37], 0, s[24:25]
	v_lshl_add_u64 v[36:37], v[36:37], 0, s[28:29]
	v_lshl_add_u64 v[38:39], v[36:37], 0, v[0:1]
	s_waitcnt lgkmcnt(0)
	s_barrier
	global_load_dwordx4 v[2:5], v[4:5], off offset:1024
	s_nop 0
	global_load_dwordx4 v[6:9], v[6:7], off
	s_nop 0
	global_load_dwordx4 v[10:13], v[12:13], off offset:1024
	s_nop 0
	global_load_dwordx4 v[14:17], v[14:15], off
	s_nop 0
	global_load_dwordx4 v[18:21], v[20:21], off offset:1024
	s_nop 0
	global_load_dwordx4 v[22:25], v[22:23], off
	s_nop 0
	global_load_dwordx4 v[26:29], v[28:29], off offset:1024
	s_nop 0
	global_load_dwordx4 v[30:33], v[30:31], off
	s_nop 0
	global_load_dwordx4 v[34:37], v[34:35], off offset:3072
	s_nop 0
	global_load_dwordx4 v[38:41], v[38:39], off offset:3136
	v_mad_u64_u32 v[78:79], s[40:41], v125, s26, v[46:47]
	v_mad_u64_u32 v[80:81], s[40:41], v127, s26, v[46:47]
	v_mad_u64_u32 v[82:83], s[40:41], v128, s26, v[46:47]
	v_mad_u64_u32 v[84:85], s[40:41], v129, s26, v[46:47]
	v_or_b32_e32 v46, 2, v50
	v_cmp_gt_i32_e64 s[44:45], v46, v126
	v_or_b32_e32 v46, 3, v50
	v_cmp_gt_i32_e64 s[46:47], v46, v126
	v_or_b32_e32 v46, 16, v50
	v_cmp_gt_i32_e64 s[48:49], v46, v126
	v_or_b32_e32 v46, 17, v50
	v_cmp_gt_i32_e64 s[50:51], v46, v126
	v_or_b32_e32 v46, 18, v50
	v_cmp_gt_i32_e64 s[52:53], v46, v126
	v_or_b32_e32 v46, 19, v50
	v_cmp_gt_i32_e64 s[54:55], v46, v126
	v_or_b32_e32 v46, 32, v50
	v_cmp_gt_i32_e64 s[56:57], v46, v126
	v_or_b32_e32 v46, 33, v50
	v_cmp_gt_i32_e64 s[58:59], v46, v126
	v_or_b32_e32 v46, 34, v50
	v_cmp_gt_i32_e64 s[60:61], v46, v126
	v_or_b32_e32 v46, 35, v50
	v_cmp_gt_i32_e64 s[62:63], v46, v126
	v_or_b32_e32 v46, 48, v50
	v_cmp_gt_i32_e64 s[64:65], v46, v126
	v_or_b32_e32 v46, 49, v50
	s_add_u32 s24, s0, s24
	v_lshl_add_u32 v133, v42, 2, s27
	v_sub_u32_e32 v54, v136, v74
	v_mad_u32_u24 v85, v45, s26, v188
	v_cmp_gt_i32_e64 s[66:67], v46, v126
	v_or_b32_e32 v46, 50, v50
	v_and_b32_e32 v42, 0xffffffc0, v42
	s_addc_u32 s26, s1, 0
	v_cmp_gt_i32_e64 s[68:69], v46, v126
	v_or_b32_e32 v46, 51, v50
	v_add_u32_e32 v138, v54, v42
	v_lshl_or_b32 v42, v43, 1, 1
	s_add_u32 s28, s24, s28
	v_mul_u32_u24_e32 v83, 0x110, v45
	v_cmp_gt_i32_e64 s[40:41], v50, v126
	v_cmp_lt_i32_e64 s[42:43], v50, v126
	v_cmp_gt_i32_e64 s[70:71], v46, v126
	v_mul_u32_u24_e32 v46, 0x90, v45
	v_lshl_or_b32 v50, v43, 5, v45
	v_lshl_or_b32 v45, v42, 4, v45
	s_addc_u32 s29, s26, 0
	v_lshrrev_b32_e32 v79, 6, v178
	v_mul_u32_u24_e32 v79, 0x480, v79
	v_lshl_add_u32 v79, v130, 1, v79
	v_add_u32_e32 v81, 0x1200, v79
	v_lshlrev_b32_e32 v47, 7, v43
	v_mul_lo_u32 v50, v50, s84
	v_lshlrev_b32_e32 v43, 6, v42
	v_mul_lo_u32 v45, v45, s84
	v_lshl_add_u64 v[86:87], s[28:29], 0, v[0:1]
	v_or_b32_e32 v0, v49, v48
	v_readlane_b32 s24, v238, 5
	v_mov_b32_e32 v88, 0
	s_mov_b32 s34, 0
	v_add3_u32 v132, 0, v49, v48
	s_waitcnt vmcnt(10)
; __device__ void mx_hgrn(const Params& P, int l, int item, char* lds) {
;     ...
;         f32x4 Sacc[2][4];
; #pragma unroll
;         for (int a = 0; a < 2; ++a)
; #pragma unroll
;             for (int dt = 0; dt < 4; ++dt) Sacc[a][dt] = (f32x4){0.f, 0.f, 0.f, 0.f};
;         __syncthreads();
;         for (int e = tid; e < 64 * 136 / 2; e += NT) ((unsigned*)ST)[e] = 0u;
;         __syncthreads();
;         u32x4 pff[4], pfq[4], pfv[2];
;         auto hg_load = [&](int cc) {
;             const int t0 = d ? SQ - 64 * (cc + 1) : 64 * cc;
; #pragma unroll
;             for (int it = 0; it < 4; ++it) {
;                 const int vi = tid + 256 * it, ii = vi >> 4, e = vi & 15, t = TROW(ii);
;                 pff[it] = *(const u32x4*)(pr + (size_t)t * PREST_LD + 512 * (1 + d) + h * 128 + e * 8);
;                 pfq[it] = *(const u32x4*)(pr + (size_t)t * PREST_LD + h * 128 + e * 8);
;             }
; #pragma unroll
;             for (int it = 0; it < 2; ++it) {
;                 const int vi = tid + 256 * it, ii = vi >> 3, e = vi & 7, t = TROW(ii);
;                 pfv[it] = *(const u32x4*)(pr + (size_t)t * PREST_LD + 1536 + h * 128 + half * 64 + e * 8);
;             }
;         };
;         hg_load(0);
; #pragma unroll 1
;         for (int c = 0; c < 32; ++c) {
;             const int t0 = d ? SQ - 64 * (c + 1) : 64 * c;
; #pragma unroll
;             for (int it = 0; it < 4; ++it) {
;                 const int vi = tid + 256 * it, ii = vi >> 4, e = vi & 15;
;                 *(u32x4*)(KT + ii * 136 + e * 8) = pff[it];
;                 *(u32x4*)(QT + ii * 136 + e * 8) = pfq[it];
;             }
; #pragma unroll
;             for (int it = 0; it < 2; ++it) {
;                 const int vi = tid + 256 * it, ii = vi >> 3, e = vi & 7;
;                 const u32x4 vv = pfv[it];
;                 VT[(e * 8 + 0) * 72 + ii] = (bf16_t)(vv.x & 0xffff); VT[(e * 8 + 1) * 72 + ii] = (bf16_t)(vv.x >> 16);
;                 VT[(e * 8 + 2) * 72 + ii] = (bf16_t)(vv.y & 0xffff); VT[(e * 8 + 3) * 72 + ii] = (bf16_t)(vv.y >> 16);
;                 VT[(e * 8 + 4) * 72 + ii] = (bf16_t)(vv.z & 0xffff); VT[(e * 8 + 5) * 72 + ii] = (bf16_t)(vv.z >> 16);
;                 VT[(e * 8 + 6) * 72 + ii] = (bf16_t)(vv.w & 0xffff); VT[(e * 8 + 7) * 72 + ii] = (bf16_t)(vv.w >> 16);
;             }
;             if (c + 1 < 32) hg_load(c + 1);
	v_sub_f32_e32 v75, 1.0, v124
	v_lshl_add_u32 v139, v42, 5, v54
	v_add_u32_e32 v140, s24, v0
	s_lshl_b32 s24, s35, 1
	s_lshl_b32 s72, s21, 1
	v_lshlrev_b32_e32 v0, 1, v44
	v_add_u32_e32 v141, v51, v52
	v_add_u32_e32 v142, v136, v46
	v_add_u32_e32 v143, v53, v47
	v_add_u32_e32 v144, v136, v50
	v_add_u32_e32 v145, v53, v43
	v_add_u32_e32 v146, v136, v45
	v_mov_b32_e32 v89, v88
	v_mov_b32_e32 v90, v88
	v_mov_b32_e32 v91, v88
	v_mov_b32_e32 v92, v88
	v_mov_b32_e32 v93, v88
	v_mov_b32_e32 v94, v88
	v_mov_b32_e32 v95, v88
	v_mov_b32_e32 v100, v88
	v_mov_b32_e32 v101, v88
	v_mov_b32_e32 v102, v88
	v_mov_b32_e32 v103, v88
	v_mov_b32_e32 v108, v88
	v_mov_b32_e32 v109, v88
	v_mov_b32_e32 v110, v88
	v_mov_b32_e32 v111, v88
	v_mov_b32_e32 v96, v88
	v_mov_b32_e32 v97, v88
	v_mov_b32_e32 v98, v88
	v_mov_b32_e32 v99, v88
	v_mov_b32_e32 v104, v88
	v_mov_b32_e32 v105, v88
	v_mov_b32_e32 v106, v88
	v_mov_b32_e32 v107, v88
	v_mov_b32_e32 v112, v88
	v_mov_b32_e32 v113, v88
	v_mov_b32_e32 v114, v88
	v_mov_b32_e32 v115, v88
	v_mov_b32_e32 v116, v88
	v_mov_b32_e32 v117, v88
	v_mov_b32_e32 v118, v88
	v_mov_b32_e32 v119, v88
.LBB0_516:
	s_add_i32 s21, s34, 1
	s_cmp_eq_u32 s34, 31
	s_waitcnt vmcnt(9)
	ds_write_b128 v78, v[2:5] offset:17408
	s_waitcnt vmcnt(8)
	ds_write_b128 v78, v[6:9]
	s_waitcnt vmcnt(7)
	ds_write_b128 v80, v[10:13] offset:17408
	s_waitcnt vmcnt(6)
	ds_write_b128 v80, v[14:17]
	s_waitcnt vmcnt(5)
	ds_write_b128 v82, v[18:21] offset:17408
	s_waitcnt vmcnt(4)
	ds_write_b128 v82, v[22:25]
	s_waitcnt vmcnt(3)
	ds_write_b128 v84, v[26:29] offset:17408
	s_waitcnt vmcnt(2)
	ds_write_b128 v84, v[30:33]
	s_waitcnt vmcnt(1)
	ds_write_b16 v79, v34 offset:45056
	ds_write_b16_d16_hi v79, v34 offset:45200
	ds_write_b16 v79, v35 offset:45344
	ds_write_b16_d16_hi v79, v35 offset:45488
	ds_write_b16 v79, v36 offset:45632
	ds_write_b16_d16_hi v79, v36 offset:45776
	ds_write_b16 v79, v37 offset:45920
	ds_write_b16_d16_hi v79, v37 offset:46064
	s_waitcnt vmcnt(0)
	ds_write_b16 v81, v38 offset:45056
	ds_write_b16_d16_hi v81, v38 offset:45200
	ds_write_b16 v81, v39 offset:45344
	ds_write_b16_d16_hi v81, v39 offset:45488
	ds_write_b16 v81, v40 offset:45632
	ds_write_b16_d16_hi v81, v40 offset:45776
	ds_write_b16 v81, v41 offset:45920
	ds_write_b16_d16_hi v81, v41 offset:46064
	s_cbranch_scc1 .LBB0_518
	s_lshl_b32 s26, s21, 6
	s_sub_i32 s27, 0x7c0, s26
	s_and_b64 s[28:29], vcc, exec
	s_cselect_b32 s27, s26, s27
	s_or_b32 s27, s27, 63
	v_sub_u32_e32 v2, s27, v125
	v_add_u32_e32 v3, s26, v125
	v_sub_u32_e32 v10, s27, v127
	v_add_u32_e32 v11, s26, v127
	v_sub_u32_e32 v18, s27, v128
	v_add_u32_e32 v19, s26, v128
	v_sub_u32_e32 v28, s27, v129
	v_add_u32_e32 v29, s26, v129
	v_cndmask_b32_e32 v2, v2, v3, vcc
	v_mov_b64_e32 v[26:27], s[0:1]
	v_cndmask_b32_e32 v10, v10, v11, vcc
	v_cndmask_b32_e32 v18, v18, v19, vcc
	v_cndmask_b32_e32 v28, v28, v29, vcc
	v_mad_i64_i32 v[2:3], s[28:29], v2, s3, v[26:27]
	v_mad_i64_i32 v[10:11], s[28:29], v10, s3, v[26:27]
	v_mad_i64_i32 v[18:19], s[28:29], v18, s3, v[26:27]
	v_mad_i64_i32 v[26:27], s[28:29], v28, s3, v[26:27]
	v_lshl_add_u64 v[4:5], v[2:3], 0, s[24:25]
	s_mov_b32 s73, s25
	v_lshl_add_u64 v[12:13], v[10:11], 0, s[24:25]
	v_lshl_add_u64 v[20:21], v[18:19], 0, s[24:25]
	v_lshl_add_u64 v[28:29], v[26:27], 0, s[24:25]
	v_sub_u32_e32 v34, s27, v130
	v_add_u32_e32 v35, s26, v130
	v_sub_u32_e32 v36, s27, v131
	v_add_u32_e32 v37, s26, v131
	v_lshl_add_u64 v[4:5], v[4:5], 0, s[72:73]
	v_lshl_add_u64 v[2:3], v[2:3], 0, s[72:73]
	v_lshl_add_u64 v[12:13], v[12:13], 0, s[72:73]
	v_lshl_add_u64 v[10:11], v[10:11], 0, s[72:73]
	v_lshl_add_u64 v[20:21], v[20:21], 0, s[72:73]
	v_lshl_add_u64 v[18:19], v[18:19], 0, s[72:73]
	v_lshl_add_u64 v[28:29], v[28:29], 0, s[72:73]
	v_lshl_add_u64 v[26:27], v[26:27], 0, s[72:73]
	v_cndmask_b32_e32 v34, v34, v35, vcc
	v_cndmask_b32_e32 v36, v36, v37, vcc
	v_lshl_add_u64 v[4:5], v[4:5], 0, v[0:1]
	v_lshl_add_u64 v[6:7], v[2:3], 0, v[0:1]
	v_lshl_add_u64 v[12:13], v[12:13], 0, v[0:1]
	v_lshl_add_u64 v[14:15], v[10:11], 0, v[0:1]
	v_lshl_add_u64 v[20:21], v[20:21], 0, v[0:1]
	v_lshl_add_u64 v[22:23], v[18:19], 0, v[0:1]
	v_lshl_add_u64 v[28:29], v[28:29], 0, v[0:1]
	v_lshl_add_u64 v[30:31], v[26:27], 0, v[0:1]
	v_mad_i64_i32 v[34:35], s[28:29], v34, s3, v[86:87]
	v_mad_i64_i32 v[38:39], s[28:29], v36, s3, v[86:87]
	global_load_dwordx4 v[2:5], v[4:5], off offset:1024
	s_nop 0
	global_load_dwordx4 v[6:9], v[6:7], off
	s_nop 0
	global_load_dwordx4 v[10:13], v[12:13], off offset:1024
	s_nop 0
	global_load_dwordx4 v[14:17], v[14:15], off
	s_nop 0
	global_load_dwordx4 v[18:21], v[20:21], off offset:1024
	s_nop 0
	global_load_dwordx4 v[22:25], v[22:23], off
	s_nop 0
	global_load_dwordx4 v[26:29], v[28:29], off offset:1024
	s_nop 0
	global_load_dwordx4 v[30:33], v[30:31], off
	s_nop 0
	global_load_dwordx4 v[34:37], v[34:35], off offset:3072
	s_nop 0
	global_load_dwordx4 v[38:41], v[38:39], off offset:3136
